# barrier protocol runs at s_setprio 3 (all waves from barrier entry to the closing workgroup barrier), static slot priority restored afterwards
# baseline (speedup 1.0000x reference)
.LBB0_8:
	s_cmp_le_i32 s17, s6
	s_cbranch_scc1 .LBB0_62
	s_setprio 3
	s_waitcnt vmcnt(0)
	s_barrier
	s_mov_b64 s[0:1], exec
	v_readlane_b32 s4, v252, 0
	v_readlane_b32 s5, v252, 1
	s_and_b64 s[4:5], s[0:1], s[4:5]
	s_mov_b64 exec, s[4:5]
	s_cbranch_execz .LBB0_61
	v_readlane_b32 s4, v254, 4
	s_waitcnt vmcnt(0) expcnt(0) lgkmcnt(0)
	s_nop 0
	v_mov_b32_e32 v2, s4
	ds_read_b32 v4, v2
	v_readlane_b32 s4, v254, 5
	s_waitcnt lgkmcnt(0)
	v_cmp_ne_u32_e32 vcc, 0, v4
	v_mov_b32_e32 v2, s4
	ds_read_b32 v2, v2
	s_cbranch_vccnz .LBB0_25
	v_readlane_b32 s6, v252, 2
	v_readlane_b32 s7, v252, 3
	s_load_dwordx2 s[4:5], s[6:7], 0x0
	s_nop 0
	s_load_dword s6, s[6:7], 0x8
	s_mov_b32 s16, 1
	s_waitcnt lgkmcnt(0)
	s_mul_i32 s13, s5, s4
	s_mul_i32 s13, s13, s6
	s_branch .LBB0_13

.Lbar_chk_done:
	s_or_b64 exec, exec, s[0:1]
	s_waitcnt lgkmcnt(0)
	s_barrier
	s_setprio 0
	v_readlane_b32 s4, v255, 49
	s_cmp_eq_u32 s4, -1
	s_cbranch_scc1 .Lprio_rst
	s_bitcmp1_b32 s4, 8
	s_cbranch_scc0 .Lprio_rst
	s_setprio 1
.Lprio_rst:
.LBB0_62:
	s_cmp_lg_u32 s17, 0
	s_cbranch_scc0 .LBB0_83
	s_add_i32 s0, s17, -1
	s_mul_hi_i32 s1, s0, 0x66666667
	s_lshr_b32 s4, s1, 31
	s_ashr_i32 s24, s1, 2
	s_add_i32 s24, s24, s4
	s_mul_i32 s1, s24, 10
	s_sub_i32 s6, s0, s1
	s_mul_i32 s38, s24, 0x1798000
	v_readlane_b32 s0, v253, 16
	s_mul_hi_i32 s27, s24, 0x1798000
	v_readlane_b32 s1, v253, 17
	s_add_u32 s0, s0, s38
	s_addc_u32 s1, s1, s27
	v_writelane_b32 v254, s0, 62
	s_mov_b64 s[4:5], -1
	v_writelane_b32 v255, s6, 0
	v_writelane_b32 v254, s1, 63
	s_mov_b64 s[0:1], 0
	s_cmp_lt_i32 s6, 6
	s_waitcnt lgkmcnt(0)
	s_mov_b64 s[10:11], 0
	s_cbranch_scc1 .LBB0_80
	v_readlane_b32 s6, v255, 0
	s_cmp_gt_i32 s6, 8
	s_cbranch_scc0 .LBB0_84
	s_mov_b64 s[4:5], 0
	s_mov_b64 s[10:11], -1
	s_cmp_eq_u32 s6, 9
	s_mov_b64 s[36:37], 0
	s_cbranch_scc0 .LBB0_67
	s_mov_b64 s[36:37], -1
	s_mov_b64 s[10:11], 0
